# v65 plus GEMM accumulator zeroing with 64 v_mov_b64 per unit instead of 127 v_mov_b32 copies
# baseline (speedup 1.0000x reference)
.LBB0_261:
	s_ashr_i32 s41, s40, 31
	v_cmp_lt_i64_e32 vcc, s[8:9], v[162:163]
	s_lshl_b64 s[8:9], s[40:41], 20
	s_add_u32 s92, s96, s8
	s_addc_u32 s93, s97, s9
	s_and_b64 s[8:9], vcc, exec
	s_cselect_b32 s10, s93, s5
	s_cselect_b32 s11, s92, s4
	s_ashr_i32 s39, s38, 31
	s_lshl_b64 s[8:9], s[38:39], 20
	v_readlane_b32 s34, v252, 58
	v_readlane_b32 s35, v252, 59
	s_add_u32 s94, s34, s8
	s_addc_u32 s95, s35, s9
	s_and_b64 s[8:9], vcc, exec
	s_cselect_b32 s20, s95, s7
	s_cselect_b32 s34, s94, s6
	s_add_u32 s4, s4, 0x80080
	s_addc_u32 s5, s5, 0
	s_add_u32 s35, s6, 0x100
	v_mov_b32_e32 v0, 0
	s_addc_u32 s36, s7, 0
	s_mov_b32 s37, -2
	v_mov_b64_e32 v[0:1], 0
	v_mov_b64_e32 v[2:3], 0
	v_mov_b64_e32 v[4:5], 0
	v_mov_b64_e32 v[6:7], 0
	v_mov_b64_e32 v[8:9], 0
	v_mov_b64_e32 v[10:11], 0
	v_mov_b64_e32 v[12:13], 0
	v_mov_b64_e32 v[14:15], 0
	v_mov_b64_e32 v[16:17], 0
	v_mov_b64_e32 v[18:19], 0
	v_mov_b64_e32 v[20:21], 0
	v_mov_b64_e32 v[22:23], 0
	v_mov_b64_e32 v[24:25], 0
	v_mov_b64_e32 v[26:27], 0
	v_mov_b64_e32 v[28:29], 0
	v_mov_b64_e32 v[30:31], 0
	v_mov_b64_e32 v[32:33], 0
	v_mov_b64_e32 v[34:35], 0
	v_mov_b64_e32 v[36:37], 0
	v_mov_b64_e32 v[38:39], 0
	v_mov_b64_e32 v[40:41], 0
	v_mov_b64_e32 v[42:43], 0
	v_mov_b64_e32 v[44:45], 0
	v_mov_b64_e32 v[46:47], 0
	v_mov_b64_e32 v[48:49], 0
	v_mov_b64_e32 v[50:51], 0
	v_mov_b64_e32 v[52:53], 0
	v_mov_b64_e32 v[54:55], 0
	v_mov_b64_e32 v[56:57], 0
	v_mov_b64_e32 v[58:59], 0
	v_mov_b64_e32 v[60:61], 0
	v_mov_b64_e32 v[62:63], 0
	v_mov_b64_e32 v[64:65], 0
	v_mov_b64_e32 v[66:67], 0
	v_mov_b64_e32 v[68:69], 0
	v_mov_b64_e32 v[70:71], 0
	v_mov_b64_e32 v[72:73], 0
	v_mov_b64_e32 v[74:75], 0
	v_mov_b64_e32 v[76:77], 0
	v_mov_b64_e32 v[78:79], 0
	v_mov_b64_e32 v[80:81], 0
	v_mov_b64_e32 v[82:83], 0
	v_mov_b64_e32 v[84:85], 0
	v_mov_b64_e32 v[86:87], 0
	v_mov_b64_e32 v[88:89], 0
	v_mov_b64_e32 v[90:91], 0
	v_mov_b64_e32 v[92:93], 0
	v_mov_b64_e32 v[94:95], 0
	v_mov_b64_e32 v[96:97], 0
	v_mov_b64_e32 v[98:99], 0
	v_mov_b64_e32 v[100:101], 0
	v_mov_b64_e32 v[102:103], 0
	v_mov_b64_e32 v[104:105], 0
	v_mov_b64_e32 v[106:107], 0
	v_mov_b64_e32 v[108:109], 0
	v_mov_b64_e32 v[110:111], 0
	v_mov_b64_e32 v[112:113], 0
	v_mov_b64_e32 v[114:115], 0
	v_mov_b64_e32 v[116:117], 0
	v_mov_b64_e32 v[118:119], 0
	v_mov_b64_e32 v[120:121], 0
	v_mov_b64_e32 v[122:123], 0
	v_mov_b64_e32 v[124:125], 0
	v_mov_b64_e32 v[126:127], 0

.LBB0_973:
	s_add_u32 s42, s16, 0x100
	v_mov_b32_e32 v0, 0
	s_addc_u32 s43, s17, 0
	s_mov_b32 s44, -2
	v_mov_b64_e32 v[0:1], 0
	v_mov_b64_e32 v[2:3], 0
	v_mov_b64_e32 v[4:5], 0
	v_mov_b64_e32 v[6:7], 0
	v_mov_b64_e32 v[8:9], 0
	v_mov_b64_e32 v[10:11], 0
	v_mov_b64_e32 v[12:13], 0
	v_mov_b64_e32 v[14:15], 0
	v_mov_b64_e32 v[16:17], 0
	v_mov_b64_e32 v[18:19], 0
	v_mov_b64_e32 v[20:21], 0
	v_mov_b64_e32 v[22:23], 0
	v_mov_b64_e32 v[24:25], 0
	v_mov_b64_e32 v[26:27], 0
	v_mov_b64_e32 v[28:29], 0
	v_mov_b64_e32 v[30:31], 0
	v_mov_b64_e32 v[32:33], 0
	v_mov_b64_e32 v[34:35], 0
	v_mov_b64_e32 v[36:37], 0
	v_mov_b64_e32 v[38:39], 0
	v_mov_b64_e32 v[40:41], 0
	v_mov_b64_e32 v[42:43], 0
	v_mov_b64_e32 v[44:45], 0
	v_mov_b64_e32 v[46:47], 0
	v_mov_b64_e32 v[48:49], 0
	v_mov_b64_e32 v[50:51], 0
	v_mov_b64_e32 v[52:53], 0
	v_mov_b64_e32 v[54:55], 0
	v_mov_b64_e32 v[56:57], 0
	v_mov_b64_e32 v[58:59], 0
	v_mov_b64_e32 v[60:61], 0
	v_mov_b64_e32 v[62:63], 0
	v_mov_b64_e32 v[64:65], 0
	v_mov_b64_e32 v[66:67], 0
	v_mov_b64_e32 v[68:69], 0
	v_mov_b64_e32 v[70:71], 0
	v_mov_b64_e32 v[72:73], 0
	v_mov_b64_e32 v[74:75], 0
	v_mov_b64_e32 v[76:77], 0
	v_mov_b64_e32 v[78:79], 0
	v_mov_b64_e32 v[80:81], 0
	v_mov_b64_e32 v[82:83], 0
	v_mov_b64_e32 v[84:85], 0
	v_mov_b64_e32 v[86:87], 0
	v_mov_b64_e32 v[88:89], 0
	v_mov_b64_e32 v[90:91], 0
	v_mov_b64_e32 v[92:93], 0
	v_mov_b64_e32 v[94:95], 0
	v_mov_b64_e32 v[96:97], 0
	v_mov_b64_e32 v[98:99], 0
	v_mov_b64_e32 v[100:101], 0
	v_mov_b64_e32 v[102:103], 0
	v_mov_b64_e32 v[104:105], 0
	v_mov_b64_e32 v[106:107], 0
	v_mov_b64_e32 v[108:109], 0
	v_mov_b64_e32 v[110:111], 0
	v_mov_b64_e32 v[112:113], 0
	v_mov_b64_e32 v[114:115], 0
	v_mov_b64_e32 v[116:117], 0
	v_mov_b64_e32 v[118:119], 0
	v_mov_b64_e32 v[120:121], 0
	v_mov_b64_e32 v[122:123], 0
	v_mov_b64_e32 v[124:125], 0
	v_mov_b64_e32 v[126:127], 0

.LBB0_1199:
	s_ashr_i32 s23, s22, 31
	v_cmp_lt_i64_e32 vcc, s[24:25], v[140:141]
	s_lshl_b64 s[24:25], s[22:23], 20
	s_add_u32 s24, s36, s24
	s_addc_u32 s25, s37, s25
	s_and_b64 s[26:27], vcc, exec
	s_cselect_b32 s4, s25, s29
	s_cselect_b32 s7, s24, s28
	s_ashr_i32 s21, s20, 31
	s_lshl_b64 s[26:27], s[20:21], 20
	s_add_u32 s26, s66, s26
	s_addc_u32 s27, s67, s27
	s_and_b64 s[34:35], vcc, exec
	s_cselect_b32 s21, s27, s31
	s_cselect_b32 s23, s26, s30
	s_add_u32 s28, s28, 0x80080
	s_addc_u32 s29, s29, 0
	s_add_u32 s54, s30, 0x100
	v_mov_b32_e32 v0, 0
	s_addc_u32 s55, s31, 0
	s_mov_b32 s56, -2
	v_mov_b64_e32 v[0:1], 0
	v_mov_b64_e32 v[2:3], 0
	v_mov_b64_e32 v[4:5], 0
	v_mov_b64_e32 v[6:7], 0
	v_mov_b64_e32 v[8:9], 0
	v_mov_b64_e32 v[10:11], 0
	v_mov_b64_e32 v[12:13], 0
	v_mov_b64_e32 v[14:15], 0
	v_mov_b64_e32 v[16:17], 0
	v_mov_b64_e32 v[18:19], 0
	v_mov_b64_e32 v[20:21], 0
	v_mov_b64_e32 v[22:23], 0
	v_mov_b64_e32 v[24:25], 0
	v_mov_b64_e32 v[26:27], 0
	v_mov_b64_e32 v[28:29], 0
	v_mov_b64_e32 v[30:31], 0
	v_mov_b64_e32 v[32:33], 0
	v_mov_b64_e32 v[34:35], 0
	v_mov_b64_e32 v[36:37], 0
	v_mov_b64_e32 v[38:39], 0
	v_mov_b64_e32 v[40:41], 0
	v_mov_b64_e32 v[42:43], 0
	v_mov_b64_e32 v[44:45], 0
	v_mov_b64_e32 v[46:47], 0
	v_mov_b64_e32 v[48:49], 0
	v_mov_b64_e32 v[50:51], 0
	v_mov_b64_e32 v[52:53], 0
	v_mov_b64_e32 v[54:55], 0
	v_mov_b64_e32 v[56:57], 0
	v_mov_b64_e32 v[58:59], 0
	v_mov_b64_e32 v[60:61], 0
	v_mov_b64_e32 v[62:63], 0
	v_mov_b64_e32 v[64:65], 0
	v_mov_b64_e32 v[66:67], 0
	v_mov_b64_e32 v[68:69], 0
	v_mov_b64_e32 v[70:71], 0
	v_mov_b64_e32 v[72:73], 0
	v_mov_b64_e32 v[74:75], 0
	v_mov_b64_e32 v[76:77], 0
	v_mov_b64_e32 v[78:79], 0
	v_mov_b64_e32 v[80:81], 0
	v_mov_b64_e32 v[82:83], 0
	v_mov_b64_e32 v[84:85], 0
	v_mov_b64_e32 v[86:87], 0
	v_mov_b64_e32 v[88:89], 0
	v_mov_b64_e32 v[90:91], 0
	v_mov_b64_e32 v[92:93], 0
	v_mov_b64_e32 v[94:95], 0
	v_mov_b64_e32 v[96:97], 0
	v_mov_b64_e32 v[98:99], 0
	v_mov_b64_e32 v[100:101], 0
	v_mov_b64_e32 v[102:103], 0
	v_mov_b64_e32 v[104:105], 0
	v_mov_b64_e32 v[106:107], 0
	v_mov_b64_e32 v[108:109], 0
	v_mov_b64_e32 v[110:111], 0
	v_mov_b64_e32 v[112:113], 0
	v_mov_b64_e32 v[114:115], 0
	v_mov_b64_e32 v[116:117], 0
	v_mov_b64_e32 v[118:119], 0
	v_mov_b64_e32 v[120:121], 0
	v_mov_b64_e32 v[122:123], 0
	v_mov_b64_e32 v[124:125], 0
	v_mov_b64_e32 v[126:127], 0

.LBB0_1401:
	s_add_u32 s67, s34, 0x100
	v_mov_b32_e32 v0, 0
	s_addc_u32 s68, s35, 0
	s_mov_b32 s69, -2
	v_mov_b64_e32 v[0:1], 0
	v_mov_b64_e32 v[2:3], 0
	v_mov_b64_e32 v[4:5], 0
	v_mov_b64_e32 v[6:7], 0
	v_mov_b64_e32 v[8:9], 0
	v_mov_b64_e32 v[10:11], 0
	v_mov_b64_e32 v[12:13], 0
	v_mov_b64_e32 v[14:15], 0
	v_mov_b64_e32 v[16:17], 0
	v_mov_b64_e32 v[18:19], 0
	v_mov_b64_e32 v[20:21], 0
	v_mov_b64_e32 v[22:23], 0
	v_mov_b64_e32 v[24:25], 0
	v_mov_b64_e32 v[26:27], 0
	v_mov_b64_e32 v[28:29], 0
	v_mov_b64_e32 v[30:31], 0
	v_mov_b64_e32 v[32:33], 0
	v_mov_b64_e32 v[34:35], 0
	v_mov_b64_e32 v[36:37], 0
	v_mov_b64_e32 v[38:39], 0
	v_mov_b64_e32 v[40:41], 0
	v_mov_b64_e32 v[42:43], 0
	v_mov_b64_e32 v[44:45], 0
	v_mov_b64_e32 v[46:47], 0
	v_mov_b64_e32 v[48:49], 0
	v_mov_b64_e32 v[50:51], 0
	v_mov_b64_e32 v[52:53], 0
	v_mov_b64_e32 v[54:55], 0
	v_mov_b64_e32 v[56:57], 0
	v_mov_b64_e32 v[58:59], 0
	v_mov_b64_e32 v[60:61], 0
	v_mov_b64_e32 v[62:63], 0
	v_mov_b64_e32 v[64:65], 0
	v_mov_b64_e32 v[66:67], 0
	v_mov_b64_e32 v[68:69], 0
	v_mov_b64_e32 v[70:71], 0
	v_mov_b64_e32 v[72:73], 0
	v_mov_b64_e32 v[74:75], 0
	v_mov_b64_e32 v[76:77], 0
	v_mov_b64_e32 v[78:79], 0
	v_mov_b64_e32 v[80:81], 0
	v_mov_b64_e32 v[82:83], 0
	v_mov_b64_e32 v[84:85], 0
	v_mov_b64_e32 v[86:87], 0
	v_mov_b64_e32 v[88:89], 0
	v_mov_b64_e32 v[90:91], 0
	v_mov_b64_e32 v[92:93], 0
	v_mov_b64_e32 v[94:95], 0
	v_mov_b64_e32 v[96:97], 0
	v_mov_b64_e32 v[98:99], 0
	v_mov_b64_e32 v[100:101], 0
	v_mov_b64_e32 v[102:103], 0
	v_mov_b64_e32 v[104:105], 0
	v_mov_b64_e32 v[106:107], 0
	v_mov_b64_e32 v[108:109], 0
	v_mov_b64_e32 v[110:111], 0
	v_mov_b64_e32 v[112:113], 0
	v_mov_b64_e32 v[114:115], 0
	v_mov_b64_e32 v[116:117], 0
	v_mov_b64_e32 v[118:119], 0
	v_mov_b64_e32 v[120:121], 0
	v_mov_b64_e32 v[122:123], 0
	v_mov_b64_e32 v[124:125], 0
	v_mov_b64_e32 v[126:127], 0
